# GLA pass A: z-gate rows, gate weights and bias requested together with k / V^T loads (one round trip instead of three)
# speedup vs baseline: 1.0042x; 1.0042x over previous
.LBB0_665:
	s_or_b64 exec, exec, s[14:15]
	v_mov_b32_e32 v0, s69
	s_waitcnt vmcnt(0) lgkmcnt(0)
	s_barrier
	ds_read_b32 v0, v0
	s_movk_i32 s4, 0x36f
	s_mov_b64 s[14:15], -1
	s_waitcnt lgkmcnt(0)
	s_barrier
	v_cmp_lt_i32_e32 vcc, s4, v0
	v_readfirstlane_b32 s3, v0
	s_cbranch_vccnz .LBB0_660
	s_cmpk_gt_i32 s3, 0x6f
	s_cbranch_scc0 .LBB0_678
	s_add_i32 s4, s3, 0xfffffd90
	s_add_i32 s30, s3, 0xffffff90
	s_lshr_b32 s4, s4, 7
	s_add_i32 s4, s4, 16
	s_lshr_b32 s5, s30, 5
	s_cmpk_lt_u32 s30, 0x200
	s_cselect_b32 s6, 3, 5
	s_cselect_b32 s4, s5, s4
	s_cselect_b32 s7, 3, 15
	s_lshr_b32 s5, s30, s6
	s_lshr_b32 s6, s30, 1
	s_lshl_b32 s11, s4, 10
	s_and_b32 s6, s7, s6
	s_and_b32 s5, s5, 3
	s_and_b32 s10, s3, 1
	s_lshl_b32 s7, s4, 8
	s_addk_i32 s11, 0xd000
	s_cmp_lt_u32 s4, 16
	s_cselect_b32 s4, s7, s11
	s_lshl_b32 s6, s6, 6
	s_add_i32 s7, s4, s6
	s_cmp_eq_u32 s10, 0
	v_mov_b32_e32 v18, v202
	s_cselect_b64 vcc, -1, 0
	s_lshl_b32 s6, s5, 6
	s_lshl_b32 s4, s5, 7
	s_add_u32 s14, s74, s4
	v_and_b32_e32 v15, 63, v18
	v_ashrrev_i32_e32 v14, 6, v18
	v_lshlrev_b32_e32 v6, 3, v14
	s_addc_u32 s15, s75, 0
	v_lshlrev_b32_e32 v0, 1, v15
	v_lshl_add_u64 v[2:3], s[14:15], 0, v[0:1]
	v_sub_u32_e32 v0, 63, v6
	v_cndmask_b32_e32 v0, v0, v6, vcc
	v_add_u32_e32 v0, s7, v0
	v_mad_i64_i32 v[4:5], s[14:15], v0, s88, v[2:3]
	v_or_b32_e32 v0, 1, v6
	global_load_ushort v16, v[4:5], off offset:512
	v_sub_u32_e32 v4, 63, v0
	v_cndmask_b32_e32 v0, v4, v0, vcc
	v_add_u32_e32 v0, s7, v0
	v_mad_i64_i32 v[4:5], s[14:15], v0, s88, v[2:3]
	v_or_b32_e32 v0, 2, v6
	global_load_ushort v21, v[4:5], off offset:512
	v_sub_u32_e32 v4, 63, v0
	v_cndmask_b32_e32 v0, v4, v0, vcc
	v_add_u32_e32 v0, s7, v0
	v_mad_i64_i32 v[4:5], s[14:15], v0, s88, v[2:3]
	v_or_b32_e32 v0, 3, v6
	global_load_ushort v17, v[4:5], off offset:512
	v_sub_u32_e32 v4, 63, v0
	v_cndmask_b32_e32 v0, v4, v0, vcc
	v_add_u32_e32 v0, s7, v0
	v_mad_i64_i32 v[4:5], s[14:15], v0, s88, v[2:3]
	v_or_b32_e32 v0, 4, v6
	global_load_ushort v22, v[4:5], off offset:512
	v_sub_u32_e32 v4, 63, v0
	v_cndmask_b32_e32 v0, v4, v0, vcc
	v_add_u32_e32 v0, s7, v0
	v_mad_i64_i32 v[4:5], s[14:15], v0, s88, v[2:3]
	v_or_b32_e32 v0, 5, v6
	global_load_ushort v19, v[4:5], off offset:512
	v_sub_u32_e32 v4, 63, v0
	v_cndmask_b32_e32 v0, v4, v0, vcc
	v_add_u32_e32 v0, s7, v0
	v_mad_i64_i32 v[4:5], s[14:15], v0, s88, v[2:3]
	v_or_b32_e32 v0, 6, v6
	global_load_ushort v23, v[4:5], off offset:512
	v_sub_u32_e32 v4, 63, v0
	v_cndmask_b32_e32 v0, v4, v0, vcc
	v_add_u32_e32 v0, s7, v0
	v_mad_i64_i32 v[4:5], s[14:15], v0, s88, v[2:3]
	v_or_b32_e32 v0, 7, v6
	global_load_ushort v20, v[4:5], off offset:512
	v_sub_u32_e32 v4, 63, v0
	v_cndmask_b32_e32 v0, v4, v0, vcc
	v_add_u32_e32 v0, s7, v0
	v_mad_i64_i32 v[2:3], s[14:15], v0, s88, v[2:3]
	v_mov_b32_e32 v0, v202
	global_load_ushort v24, v[2:3], off offset:512
	s_lshl_b32 s24, s5, 8
	v_ashrrev_i32_e32 v6, 3, v0
	v_and_b32_e32 v11, -16, v6
	v_and_b32_e32 v10, 0x7f, v0
	v_sub_u32_e32 v0, 63, v11
	v_sub_u32_e32 v2, 62, v11
	v_or_b32_e32 v3, 1, v11
	v_cndmask_b32_e32 v0, v0, v11, vcc
	v_cndmask_b32_e32 v2, v2, v3, vcc
	v_add_u32_e32 v0, s7, v0
	v_add_u32_e32 v7, s7, v2
	v_mov_b64_e32 v[2:3], s[74:75]
	v_mad_i64_i32 v[4:5], s[14:15], v0, s88, v[2:3]
	s_mov_b32 s25, s31
	v_lshl_add_u64 v[4:5], v[4:5], 0, s[24:25]
	v_lshlrev_b32_e32 v0, 1, v10
	v_lshl_add_u64 v[4:5], v[4:5], 0, v[0:1]
	global_load_ushort v8, v[4:5], off offset:1024
	v_mad_i64_i32 v[4:5], s[14:15], v7, s88, v[2:3]
	v_lshl_add_u64 v[4:5], v[4:5], 0, s[24:25]
	v_lshl_add_u64 v[4:5], v[4:5], 0, v[0:1]
	global_load_ushort v7, v[4:5], off offset:1024
	v_or_b32_e32 v4, 2, v11
	v_sub_u32_e32 v5, 63, v4
	v_cndmask_b32_e32 v5, v5, v4, vcc
	v_sub_u32_e32 v4, 62, v4
	v_or_b32_e32 v9, 3, v11
	v_add_u32_e32 v5, s7, v5
	v_cndmask_b32_e32 v4, v4, v9, vcc
	v_add_u32_e32 v9, s7, v4
	v_mad_i64_i32 v[4:5], s[14:15], v5, s88, v[2:3]
	v_lshl_add_u64 v[4:5], v[4:5], 0, s[24:25]
	v_lshl_add_u64 v[4:5], v[4:5], 0, v[0:1]
	global_load_ushort v12, v[4:5], off offset:1024
	v_mad_i64_i32 v[4:5], s[14:15], v9, s88, v[2:3]
	v_lshl_add_u64 v[4:5], v[4:5], 0, s[24:25]
	v_lshl_add_u64 v[4:5], v[4:5], 0, v[0:1]
	global_load_ushort v9, v[4:5], off offset:1024
	v_or_b32_e32 v4, 4, v11
	v_sub_u32_e32 v5, 63, v4
	v_cndmask_b32_e32 v5, v5, v4, vcc
	v_sub_u32_e32 v4, 62, v4
	v_or_b32_e32 v13, 5, v11
	v_add_u32_e32 v5, s7, v5
	v_cndmask_b32_e32 v4, v4, v13, vcc
	v_add_u32_e32 v13, s7, v4
	v_mad_i64_i32 v[4:5], s[14:15], v5, s88, v[2:3]
	v_lshl_add_u64 v[4:5], v[4:5], 0, s[24:25]
	v_lshl_add_u64 v[4:5], v[4:5], 0, v[0:1]
	global_load_ushort v25, v[4:5], off offset:1024
	v_mad_i64_i32 v[4:5], s[14:15], v13, s88, v[2:3]
	v_lshl_add_u64 v[4:5], v[4:5], 0, s[24:25]
	v_lshl_add_u64 v[4:5], v[4:5], 0, v[0:1]
	global_load_ushort v13, v[4:5], off offset:1024
	v_or_b32_e32 v4, 6, v11
	v_sub_u32_e32 v5, 63, v4
	v_cndmask_b32_e32 v5, v5, v4, vcc
	v_sub_u32_e32 v4, 62, v4
	v_or_b32_e32 v26, 7, v11
	v_add_u32_e32 v5, s7, v5
	v_cndmask_b32_e32 v4, v4, v26, vcc
	v_add_u32_e32 v26, s7, v4
	v_mad_i64_i32 v[4:5], s[14:15], v5, s88, v[2:3]
	v_lshl_add_u64 v[4:5], v[4:5], 0, s[24:25]
	v_lshl_add_u64 v[4:5], v[4:5], 0, v[0:1]
	global_load_ushort v27, v[4:5], off offset:1024
	v_mad_i64_i32 v[4:5], s[14:15], v26, s88, v[2:3]
	v_lshl_add_u64 v[4:5], v[4:5], 0, s[24:25]
	v_lshl_add_u64 v[4:5], v[4:5], 0, v[0:1]
	global_load_ushort v26, v[4:5], off offset:1024
	v_or_b32_e32 v4, 8, v11
	v_sub_u32_e32 v5, 63, v4
	v_cndmask_b32_e32 v5, v5, v4, vcc
	v_sub_u32_e32 v4, 62, v4
	v_or_b32_e32 v28, 9, v11
	v_add_u32_e32 v5, s7, v5
	v_cndmask_b32_e32 v4, v4, v28, vcc
	v_add_u32_e32 v28, s7, v4
	v_mad_i64_i32 v[4:5], s[14:15], v5, s88, v[2:3]
	v_lshl_add_u64 v[4:5], v[4:5], 0, s[24:25]
	v_lshl_add_u64 v[4:5], v[4:5], 0, v[0:1]
	global_load_ushort v29, v[4:5], off offset:1024
	v_mad_i64_i32 v[4:5], s[14:15], v28, s88, v[2:3]
	v_lshl_add_u64 v[4:5], v[4:5], 0, s[24:25]
	v_lshl_add_u64 v[4:5], v[4:5], 0, v[0:1]
	global_load_ushort v28, v[4:5], off offset:1024
	v_or_b32_e32 v4, 10, v11
	v_sub_u32_e32 v5, 63, v4
	v_cndmask_b32_e32 v5, v5, v4, vcc
	v_sub_u32_e32 v4, 62, v4
	v_or_b32_e32 v30, 11, v11
	v_add_u32_e32 v5, s7, v5
	v_cndmask_b32_e32 v4, v4, v30, vcc
	v_add_u32_e32 v30, s7, v4
	v_mad_i64_i32 v[4:5], s[14:15], v5, s88, v[2:3]
	v_lshl_add_u64 v[4:5], v[4:5], 0, s[24:25]
	v_lshl_add_u64 v[4:5], v[4:5], 0, v[0:1]
	global_load_ushort v31, v[4:5], off offset:1024
	v_mad_i64_i32 v[4:5], s[14:15], v30, s88, v[2:3]
	v_lshl_add_u64 v[4:5], v[4:5], 0, s[24:25]
	v_lshl_add_u64 v[4:5], v[4:5], 0, v[0:1]
	global_load_ushort v30, v[4:5], off offset:1024
	v_or_b32_e32 v4, 12, v11
	v_sub_u32_e32 v5, 63, v4
	v_cndmask_b32_e32 v5, v5, v4, vcc
	v_sub_u32_e32 v4, 62, v4
	v_or_b32_e32 v32, 13, v11
	v_add_u32_e32 v5, s7, v5
	v_cndmask_b32_e32 v4, v4, v32, vcc
	v_add_u32_e32 v32, s7, v4
	v_mad_i64_i32 v[4:5], s[14:15], v5, s88, v[2:3]
	v_lshl_add_u64 v[4:5], v[4:5], 0, s[24:25]
	v_lshl_add_u64 v[4:5], v[4:5], 0, v[0:1]
	global_load_ushort v33, v[4:5], off offset:1024
	v_mad_i64_i32 v[4:5], s[14:15], v32, s88, v[2:3]
	v_lshl_add_u64 v[4:5], v[4:5], 0, s[24:25]
	v_lshl_add_u64 v[4:5], v[4:5], 0, v[0:1]
	global_load_ushort v32, v[4:5], off offset:1024
	v_or_b32_e32 v4, 14, v11
	v_sub_u32_e32 v5, 63, v4
	v_cndmask_b32_e32 v5, v5, v4, vcc
	v_sub_u32_e32 v4, 62, v4
	v_or_b32_e32 v6, 15, v6
	v_cndmask_b32_e32 v4, v4, v6, vcc
	v_add_u32_e32 v5, s7, v5
	v_add_u32_e32 v6, s7, v4
	v_mad_i64_i32 v[4:5], s[14:15], v5, s88, v[2:3]
	v_mad_i64_i32 v[2:3], s[14:15], v6, s88, v[2:3]
	v_lshl_add_u64 v[4:5], v[4:5], 0, s[24:25]
	v_lshl_add_u64 v[2:3], v[2:3], 0, s[24:25]
	v_lshl_add_u64 v[4:5], v[4:5], 0, v[0:1]
	v_lshl_add_u64 v[2:3], v[2:3], 0, v[0:1]
	global_load_ushort v34, v[4:5], off offset:1024
	global_load_ushort v0, v[2:3], off offset:1024
	v_readlane_b32 s96, v253, 54
	v_readlane_b32 s97, v253, 55
	s_lshl_b32 s98, s10, 6
	s_add_u32 s96, s96, s98
	s_addc_u32 s97, s97, 0
	v_and_b32_e32 v150, 15, v202
	v_lshlrev_b32_e32 v150, 2, v150
	v_mov_b32_e32 v151, 0
	v_ashrrev_i32_e32 v152, 4, v202
	v_lshl_add_u64 v[150:151], s[96:97], 0, v[150:151]
	v_add_u32_e32 v153, 32, v152
	v_sub_u32_e32 v154, 63, v152
	v_sub_u32_e32 v155, 63, v153
	v_cndmask_b32_e32 v152, v154, v152, vcc
	v_cndmask_b32_e32 v153, v155, v153, vcc
	v_add_u32_e32 v152, s7, v152
	v_add_u32_e32 v153, s7, v153
	v_lshlrev_b32_e32 v156, 7, v152
	v_mov_b32_e32 v157, 0
	v_lshlrev_b32_e32 v158, 7, v153
	v_mov_b32_e32 v159, 0
	v_lshl_add_u64 v[156:157], v[150:151], 0, v[156:157]
	v_lshl_add_u64 v[158:159], v[150:151], 0, v[158:159]
	s_cmp_eq_u32 s10, 0
	s_movk_i32 s98, 0x68
	s_cselect_b32 s98, s98, 0x78
	global_load_dword v130, v[156:157], off
	global_load_dword v131, v[158:159], off
	s_add_u32 s96, s8, s98
	s_addc_u32 s97, s9, 0
	s_load_dwordx2 s[96:97], s[96:97], 0x0
	s_add_u32 s98, s8, s98
	s_addc_u32 s99, s9, 0
	s_load_dwordx2 s[98:99], s[98:99], 0x8
	v_and_b32_e32 v160, 63, v202
	v_mov_b32_e32 v162, s6
	v_lshlrev_b32_e32 v161, 2, v160
	v_mov_b32_e32 v163, 0
	v_lshl_add_u32 v162, v162, 2, v161
	v_mov_b32_e32 v164, 0x1000
	v_mov_b32_e32 v165, 0
	s_waitcnt lgkmcnt(0)
	s_add_u32 s96, s96, s22
	s_addc_u32 s97, s97, s23
	v_lshl_add_u64 v[162:163], s[96:97], 0, v[162:163]
	s_nop 0
	v_lshl_add_u64 v[166:167], v[162:163], 0, v[164:165]
	global_load_dword v132, v[162:163], off
	global_load_dword v133, v[162:163], off offset:1024
	global_load_dword v134, v[162:163], off offset:2048
	global_load_dword v135, v[162:163], off offset:3072
	v_lshl_add_u64 v[162:163], v[166:167], 0, v[164:165]
	global_load_dword v136, v[166:167], off
	global_load_dword v137, v[166:167], off offset:1024
	global_load_dword v138, v[166:167], off offset:2048
	global_load_dword v139, v[166:167], off offset:3072
	v_lshl_add_u64 v[166:167], v[162:163], 0, v[164:165]
	global_load_dword v140, v[162:163], off
	global_load_dword v141, v[162:163], off offset:1024
	global_load_dword v142, v[162:163], off offset:2048
	global_load_dword v143, v[162:163], off offset:3072
	v_readlane_b32 s96, v254, 41
	global_load_dword v144, v[166:167], off
	global_load_dword v145, v[166:167], off offset:1024
	global_load_dword v146, v[166:167], off offset:2048
	global_load_dword v147, v[166:167], off offset:3072
	s_or_b32 s96, s6, s96
	v_mov_b32_e32 v169, 0
	v_or_b32_e32 v168, s96, v160
	s_nop 0
	v_lshl_add_u64 v[168:169], v[168:169], 2, s[98:99]
	s_nop 0
	global_load_dword v148, v[168:169], off
	s_waitcnt vmcnt(31)
	v_lshl_or_b32 v3, v9, 16, v12
	v_lshl_or_b32 v2, v7, 16, v8
	s_waitcnt vmcnt(29)
	v_lshl_or_b32 v4, v13, 16, v25
	s_movk_i32 s4, 0x400
	s_waitcnt vmcnt(27)
	v_lshl_or_b32 v5, v26, 16, v27
	s_waitcnt vmcnt(25)
	v_lshl_or_b32 v6, v28, 16, v29
	s_waitcnt vmcnt(23)
	v_lshl_or_b32 v7, v30, 16, v31
	s_waitcnt vmcnt(21)
	v_lshl_or_b32 v8, v32, 16, v33
	s_waitcnt vmcnt(19)
	v_lshl_or_b32 v9, v0, 16, v34
	v_mul_u32_u24_e32 v0, 0x90, v10
	v_lshlrev_b32_e32 v10, 1, v11
	v_add3_u32 v0, 0, v0, v10
	ds_write_b128 v0, v[2:5] offset:9216
	ds_write_b128 v0, v[6:9] offset:9232
	v_mov_b32_e32 v2, v202
	s_nop 0
	s_waitcnt vmcnt(17)
	s_movk_i32 s4, 0x6c00
	v_lshl_add_u32 v9, v2, 2, s4
	ds_write2st64_b32 v9, v130, v131 offset1:8
.LBB0_675:
	s_and_b64 s[10:11], vcc, exec
	s_movk_i32 s4, 0x68
	s_cselect_b32 s4, s4, 0x78
	s_add_u32 s10, s8, s4
	s_addc_u32 s11, s9, 0
	s_waitcnt lgkmcnt(0)
	s_barrier
	v_and_b32_e32 v3, 63, v2
	v_lshlrev_b32_e32 v0, 2, v3
	s_waitcnt lgkmcnt(0)
	s_add_u32 s4, s10, s22
	s_addc_u32 s5, s11, s23
	s_lshl_b32 s7, s6, 2
	s_add_u32 s10, s4, s7
	s_addc_u32 s11, s5, 0
	v_lshl_add_u64 v[8:9], s[10:11], 0, v[0:1]
	v_add_co_u32_e64 v34, s[40:41], s37, v8
	s_and_b64 s[14:15], vcc, exec
	s_nop 0
	v_addc_co_u32_e64 v35, s[40:41], 0, v9, s[40:41]
	s_movk_i32 s4, 0x70
	v_add_co_u32_e64 v36, s[40:41], s85, v8
	s_cselect_b32 s4, s4, 0x80
	s_nop 0
	v_addc_co_u32_e64 v37, s[40:41], 0, v9, s[40:41]
	s_add_u32 s14, s8, s4
	v_add_co_u32_e64 v26, s[40:41], s68, v8
	s_addc_u32 s15, s9, 0
	v_addc_co_u32_e64 v27, s[40:41], 0, v9, s[40:41]
	v_readlane_b32 s4, v254, 41
	s_or_b32 s4, s6, s4
	v_or_b32_e32 v26, s4, v3
	v_mov_b32_e32 v27, v1
	s_waitcnt lgkmcnt(0)
	v_lshl_add_u64 v[26:27], v[26:27], 2, s[14:15]
	s_nop 0
	s_waitcnt vmcnt(0)
	v_mov_b32_e32 v29, v132
	v_mov_b32_e32 v30, v133
	v_mov_b32_e32 v31, v134
	v_mov_b32_e32 v32, v135
	v_mov_b32_e32 v28, v136
	v_mov_b32_e32 v27, v137
	v_mov_b32_e32 v12, v138
	v_mov_b32_e32 v13, v139
	v_mov_b32_e32 v6, v140
	v_mov_b32_e32 v7, v141
	v_mov_b32_e32 v4, v142
	v_mov_b32_e32 v5, v143
	v_mov_b32_e32 v8, v144
	v_mov_b32_e32 v9, v145
	v_mov_b32_e32 v10, v146
	v_mov_b32_e32 v11, v147
	v_mov_b32_e32 v26, v148
	v_ashrrev_i32_e32 v3, 6, v2
	v_lshl_add_u32 v25, v3, 9, 0
	ds_read_b128 v[34:37], v25 offset:27664
	ds_read_b128 v[38:41], v25 offset:27680
	ds_read_b128 v[42:45], v25 offset:27696
	ds_read_b128 v[46:49], v25 offset:27648
	s_mov_b32 s4, 0x3d800000
	v_lshl_add_u32 v2, v2, 2, 0
	v_add_u32_e32 v0, 0, v0
	v_readlane_b32 s5, v254, 42
	s_waitcnt vmcnt(15) lgkmcnt(2)
	v_pk_mul_f32 v[38:39], v[6:7], v[38:39]
	s_waitcnt vmcnt(13)
	v_pk_mul_f32 v[40:41], v[4:5], v[40:41]
	s_waitcnt vmcnt(11)
	v_pk_mul_f32 v[36:37], v[12:13], v[36:37]
	s_waitcnt vmcnt(9) lgkmcnt(1)
	v_pk_mul_f32 v[42:43], v[8:9], v[42:43]
	s_waitcnt vmcnt(5) lgkmcnt(0)
	v_fma_f32 v33, v29, v46, v26
	s_waitcnt vmcnt(4)
	v_fmac_f32_e32 v33, v30, v47
	s_waitcnt vmcnt(3)
	v_fmac_f32_e32 v33, v31, v48
	s_waitcnt vmcnt(2)
	v_fmac_f32_e32 v33, v32, v49
	s_waitcnt vmcnt(1)
	v_fmac_f32_e32 v33, v28, v34
	s_waitcnt vmcnt(0)
	v_fmac_f32_e32 v33, v27, v35
	v_add_f32_e32 v33, v33, v36
	v_add_f32_e32 v33, v33, v37
	v_add_f32_e32 v33, v33, v38
	v_add_f32_e32 v33, v33, v39
	v_add_f32_e32 v33, v33, v40
	v_add_f32_e32 v33, v33, v41
	v_add_f32_e32 v33, v33, v42
	v_pk_mul_f32 v[44:45], v[10:11], v[44:45]
	v_add_f32_e32 v33, v33, v43
	v_add_f32_e32 v33, v33, v44
	v_add_f32_e32 v33, v33, v45
	v_mul_f32_e64 v34, |v33|, s90
	v_exp_f32_e32 v38, v34
	v_min_f32_e32 v33, 0, v33
	v_add_f32_e32 v36, 1.0, v38
	v_add_f32_e32 v37, -1.0, v36
	v_frexp_mant_f32_e32 v39, v36
	v_cvt_f64_f32_e32 v[34:35], v36
	v_sub_f32_e32 v40, v37, v36
	v_frexp_exp_i32_f64_e32 v34, v[34:35]
	v_cmp_gt_f32_e32 vcc, s36, v39
	v_sub_f32_e32 v37, v38, v37
	v_add_f32_e32 v35, 1.0, v40
	v_subbrev_co_u32_e32 v34, vcc, 0, v34, vcc
	v_add_f32_e32 v35, v37, v35
	v_sub_u32_e32 v37, 0, v34
	v_cvt_f32_i32_e32 v34, v34
	v_ldexp_f32 v36, v36, v37
	v_ldexp_f32 v35, v35, v37
	v_add_f32_e32 v37, -1.0, v36
	v_add_f32_e32 v39, 1.0, v36
	v_add_f32_e32 v40, 1.0, v37
	v_add_f32_e32 v41, -1.0, v39
	v_sub_f32_e32 v40, v36, v40
	v_sub_f32_e32 v36, v36, v41
	v_mul_f32_e32 v41, 0x3f317218, v34
	v_add_f32_e32 v40, v35, v40
	v_add_f32_e32 v35, v35, v36
	v_fma_f32 v36, v34, s78, -v41
	v_add_f32_e32 v42, v37, v40
	v_add_f32_e32 v43, v39, v35
	v_fmac_f32_e32 v36, 0xb102e308, v34
	v_sub_f32_e32 v34, v42, v37
	v_sub_f32_e32 v37, v43, v39
	v_rcp_f32_e32 v39, v43
	v_add_f32_e32 v44, v41, v36
	v_sub_f32_e32 v35, v35, v37
	v_sub_f32_e32 v37, v44, v41
	v_sub_f32_e32 v36, v36, v37
	v_mul_f32_e32 v37, v42, v39
	v_sub_f32_e32 v34, v40, v34
	v_mul_f32_e32 v40, v43, v37
	v_fma_f32 v41, v37, v43, -v40
	v_fmac_f32_e32 v41, v37, v35
	v_add_f32_e32 v45, v40, v41
	v_sub_f32_e32 v46, v42, v45
	v_sub_f32_e32 v40, v45, v40
	v_sub_f32_e32 v42, v42, v46
	v_sub_f32_e32 v40, v40, v41
	v_sub_f32_e32 v41, v42, v45
	v_add_f32_e32 v34, v34, v41
	v_add_f32_e32 v34, v40, v34
	v_add_f32_e32 v40, v46, v34
	v_mul_f32_e32 v41, v39, v40
	v_sub_f32_e32 v42, v46, v40
	v_mul_f32_e32 v45, v43, v41
	v_add_f32_e32 v34, v34, v42
	v_add_f32_e32 v42, v37, v41
	v_fma_f32 v43, v41, v43, -v45
	v_sub_f32_e32 v37, v42, v37
	v_fmac_f32_e32 v43, v41, v35
	v_sub_f32_e32 v35, v41, v37
	v_add_f32_e32 v37, v45, v43
	v_sub_f32_e32 v41, v37, v45
	v_sub_f32_e32 v45, v40, v37
	v_sub_f32_e32 v40, v40, v45
	v_sub_f32_e32 v37, v40, v37
	v_sub_f32_e32 v41, v41, v43
	v_add_f32_e32 v34, v34, v37
	v_add_f32_e32 v34, v41, v34
	v_add_f32_e32 v34, v45, v34
	v_mul_f32_e32 v34, v39, v34
	v_add_f32_e32 v34, v35, v34
	v_add_f32_e32 v35, v42, v34
	v_mul_f32_e32 v37, v35, v35
	v_fmamk_f32 v41, v37, 0x3e9b6dac, v204
	v_sub_f32_e32 v39, v35, v42
	v_ldexp_f32 v40, v35, 1
	v_mul_f32_e32 v35, v35, v37
	v_fmaak_f32 v37, v37, v41, 0x3f2aaada
	v_mul_f32_e32 v35, v35, v37
	v_add_f32_e32 v37, v40, v35
	v_sub_f32_e32 v34, v34, v39
	v_sub_f32_e32 v39, v37, v40
	v_ldexp_f32 v34, v34, 1
	v_sub_f32_e32 v35, v35, v39
	v_add_f32_e32 v34, v34, v35
	v_add_f32_e32 v35, v37, v34
	v_sub_f32_e32 v37, v35, v37
	v_add_f32_e32 v39, v44, v35
	v_sub_f32_e32 v34, v34, v37
	v_sub_f32_e32 v37, v39, v44
	v_sub_f32_e32 v40, v39, v37
	v_sub_f32_e32 v35, v35, v37
	v_add_f32_e32 v37, v36, v34
	v_sub_f32_e32 v40, v44, v40
	v_add_f32_e32 v35, v35, v40
	v_sub_f32_e32 v40, v37, v36
	v_sub_f32_e32 v41, v37, v40
	v_sub_f32_e32 v36, v36, v41
	v_sub_f32_e32 v34, v34, v40
	v_add_f32_e32 v35, v37, v35
	v_add_f32_e32 v34, v34, v36
	v_add_f32_e32 v36, v39, v35
	v_sub_f32_e32 v37, v36, v39
	v_sub_f32_e32 v35, v35, v37
	v_add_f32_e32 v34, v34, v35
	v_add_f32_e32 v34, v36, v34
	v_cmp_neq_f32_e32 vcc, s79, v38
	s_nop 1
	v_cndmask_b32_e32 v34, v211, v34, vcc
	v_cmp_ngt_f32_e32 vcc, -1.0, v38
	s_nop 1
	v_cndmask_b32_e32 v39, v212, v34, vcc
	ds_read_b128 v[34:37], v25 offset:27712
	v_cmp_neq_f32_e32 vcc, -1.0, v38
	s_nop 1
	v_cndmask_b32_e32 v39, v213, v39, vcc
	v_cmp_lt_f32_e64 vcc, |v38|, s2
	s_nop 1
	v_cndmask_b32_e32 v42, v39, v38, vcc
	ds_read_b128 v[38:41], v25 offset:27728
	s_waitcnt lgkmcnt(1)
	v_fma_f32 v43, v29, v34, v26
	v_fmac_f32_e32 v43, v30, v35
	v_fmac_f32_e32 v43, v31, v36
	v_fmac_f32_e32 v43, v32, v37
	ds_read_b128 v[34:37], v25 offset:27744
	s_waitcnt lgkmcnt(1)
	v_fmac_f32_e32 v43, v28, v38
	v_fmac_f32_e32 v43, v27, v39
	v_pk_mul_f32 v[38:39], v[12:13], v[40:41]
	v_sub_f32_e32 v33, v33, v42
	v_add_f32_e32 v38, v43, v38
	v_add_f32_e32 v43, v38, v39
	ds_read_b128 v[38:41], v25 offset:27760
	s_waitcnt lgkmcnt(1)
	v_pk_mul_f32 v[34:35], v[6:7], v[34:35]
	v_fma_f32 v33, v33, s4, 0
	v_add_f32_e32 v34, v43, v34
	v_add_f32_e32 v43, v34, v35
	v_pk_mul_f32 v[34:35], v[4:5], v[36:37]
	s_nop 0
	v_add_f32_e32 v34, v43, v34
	v_add_f32_e32 v36, v34, v35
	s_waitcnt lgkmcnt(0)
	v_pk_mul_f32 v[34:35], v[8:9], v[38:39]
	s_nop 0
	v_add_f32_e32 v34, v36, v34
	v_add_f32_e32 v36, v34, v35
	v_pk_mul_f32 v[34:35], v[10:11], v[40:41]
	s_nop 0
	v_add_f32_e32 v34, v36, v34
	v_add_f32_e32 v34, v34, v35
	v_mul_f32_e64 v35, |v34|, s90
	v_exp_f32_e32 v38, v35
	v_min_f32_e32 v42, 0, v34
	v_add_f32_e32 v36, 1.0, v38
	v_add_f32_e32 v34, -1.0, v36
	v_sub_f32_e32 v35, v34, v36
	v_add_f32_e32 v35, 1.0, v35
	v_sub_f32_e32 v34, v38, v34
	v_add_f32_e32 v37, v34, v35
	v_frexp_mant_f32_e32 v39, v36
	v_cvt_f64_f32_e32 v[34:35], v36
	v_frexp_exp_i32_f64_e32 v34, v[34:35]
	v_cmp_gt_f32_e32 vcc, s36, v39
	s_nop 1
	v_subbrev_co_u32_e32 v34, vcc, 0, v34, vcc
	v_sub_u32_e32 v35, 0, v34
	v_ldexp_f32 v36, v36, v35
	v_ldexp_f32 v35, v37, v35
	v_add_f32_e32 v37, -1.0, v36
	v_add_f32_e32 v41, 1.0, v36
	v_add_f32_e32 v39, 1.0, v37
	v_add_f32_e32 v43, -1.0, v41
	v_sub_f32_e32 v39, v36, v39
	v_sub_f32_e32 v36, v36, v43
	v_add_f32_e32 v39, v35, v39
	v_add_f32_e32 v35, v35, v36
	v_add_f32_e32 v36, v41, v35
	v_rcp_f32_e32 v43, v36
	v_add_f32_e32 v40, v37, v39
	v_sub_f32_e32 v37, v40, v37
	v_sub_f32_e32 v37, v39, v37
	v_sub_f32_e32 v39, v36, v41
	v_sub_f32_e32 v35, v35, v39
	v_mul_f32_e32 v39, v40, v43
	v_mul_f32_e32 v41, v36, v39
	v_fma_f32 v44, v39, v36, -v41
	v_fmac_f32_e32 v44, v39, v35
	v_add_f32_e32 v45, v41, v44
	v_sub_f32_e32 v46, v40, v45
	v_sub_f32_e32 v40, v40, v46
	v_sub_f32_e32 v41, v45, v41
	v_sub_f32_e32 v40, v40, v45
	v_add_f32_e32 v37, v37, v40
	v_sub_f32_e32 v40, v41, v44
	v_add_f32_e32 v37, v40, v37
	v_add_f32_e32 v40, v46, v37
	v_mul_f32_e32 v41, v43, v40
	v_mul_f32_e32 v44, v36, v41
	v_fma_f32 v36, v41, v36, -v44
	v_fmac_f32_e32 v36, v41, v35
	v_sub_f32_e32 v35, v46, v40
	v_add_f32_e32 v35, v37, v35
	v_add_f32_e32 v37, v44, v36
	v_sub_f32_e32 v45, v40, v37
	v_sub_f32_e32 v40, v40, v45
	v_sub_f32_e32 v44, v37, v44
	v_sub_f32_e32 v37, v40, v37
	v_add_f32_e32 v35, v35, v37
	v_sub_f32_e32 v36, v44, v36
	v_cvt_f32_i32_e32 v34, v34
	v_add_f32_e32 v35, v36, v35
	v_add_f32_e32 v36, v39, v41
	v_add_f32_e32 v35, v45, v35
	v_sub_f32_e32 v37, v36, v39
	v_mul_f32_e32 v35, v43, v35
	v_sub_f32_e32 v37, v41, v37
	v_add_f32_e32 v35, v37, v35
	v_mul_f32_e32 v41, 0x3f317218, v34
	v_add_f32_e32 v37, v36, v35
	v_fma_f32 v43, v34, s78, -v41
	v_mul_f32_e32 v39, v37, v37
	v_fmac_f32_e32 v43, 0xb102e308, v34
	v_sub_f32_e32 v34, v37, v36
	v_fmamk_f32 v40, v39, 0x3e9b6dac, v204
	v_sub_f32_e32 v34, v35, v34
	v_add_f32_e32 v35, v41, v43
	v_fmaak_f32 v40, v39, v40, 0x3f2aaada
	v_sub_f32_e32 v36, v35, v41
	v_ldexp_f32 v41, v37, 1
	v_mul_f32_e32 v37, v37, v39
	v_mul_f32_e32 v37, v37, v40
	v_add_f32_e32 v39, v41, v37
	v_sub_f32_e32 v40, v39, v41
	v_ldexp_f32 v34, v34, 1
	v_sub_f32_e32 v37, v37, v40
	v_add_f32_e32 v34, v34, v37
	v_add_f32_e32 v37, v39, v34
	v_sub_f32_e32 v39, v37, v39
	v_sub_f32_e32 v34, v34, v39
	v_add_f32_e32 v39, v35, v37
	v_sub_f32_e32 v40, v39, v35
	v_sub_f32_e32 v41, v39, v40
	v_sub_f32_e32 v36, v43, v36
	v_sub_f32_e32 v35, v35, v41
	v_sub_f32_e32 v37, v37, v40
	v_add_f32_e32 v35, v37, v35
	v_add_f32_e32 v37, v36, v34
	v_sub_f32_e32 v40, v37, v36
	v_sub_f32_e32 v41, v37, v40
	v_sub_f32_e32 v36, v36, v41
	v_sub_f32_e32 v34, v34, v40
	v_add_f32_e32 v35, v37, v35
	v_add_f32_e32 v34, v34, v36
	v_add_f32_e32 v36, v39, v35
	v_sub_f32_e32 v37, v36, v39
	v_sub_f32_e32 v35, v35, v37
	v_add_f32_e32 v34, v34, v35
	v_add_f32_e32 v34, v36, v34
	v_cmp_neq_f32_e32 vcc, s79, v38
	s_nop 1
	v_cndmask_b32_e32 v34, v211, v34, vcc
	v_cmp_ngt_f32_e32 vcc, -1.0, v38
	s_nop 1
	v_cndmask_b32_e32 v39, v212, v34, vcc
	ds_read_b128 v[34:37], v25 offset:27776
	v_cmp_neq_f32_e32 vcc, -1.0, v38
	s_nop 1
	v_cndmask_b32_e32 v39, v213, v39, vcc
	v_cmp_lt_f32_e64 vcc, |v38|, s2
	s_nop 1
	v_cndmask_b32_e32 v43, v39, v38, vcc
	ds_read_b128 v[38:41], v25 offset:27792
	s_waitcnt lgkmcnt(1)
	v_fma_f32 v44, v29, v34, v26
	v_fmac_f32_e32 v44, v30, v35
	v_fmac_f32_e32 v44, v31, v36
	v_fmac_f32_e32 v44, v32, v37
	ds_read_b128 v[34:37], v25 offset:27808
	s_waitcnt lgkmcnt(1)
	v_fmac_f32_e32 v44, v28, v38
	v_fmac_f32_e32 v44, v27, v39
	v_pk_mul_f32 v[38:39], v[12:13], v[40:41]
	s_nop 0
	v_add_f32_e32 v38, v44, v38
	v_add_f32_e32 v44, v38, v39
	ds_read_b128 v[38:41], v25 offset:27824
	s_waitcnt lgkmcnt(1)
	v_pk_mul_f32 v[34:35], v[6:7], v[34:35]
	s_nop 0
	v_add_f32_e32 v34, v44, v34
	v_add_f32_e32 v44, v34, v35
	v_pk_mul_f32 v[34:35], v[4:5], v[36:37]
	s_nop 0
	v_add_f32_e32 v34, v44, v34
	v_add_f32_e32 v36, v34, v35
	s_waitcnt lgkmcnt(0)
	v_pk_mul_f32 v[34:35], v[8:9], v[38:39]
	s_nop 0
	v_add_f32_e32 v34, v36, v34
	v_add_f32_e32 v36, v34, v35
	v_pk_mul_f32 v[34:35], v[10:11], v[40:41]
	s_nop 0
	v_add_f32_e32 v34, v36, v34
	v_add_f32_e32 v35, v34, v35
	v_mul_f32_e64 v34, |v35|, s90
	v_exp_f32_e32 v40, v34
	v_sub_f32_e32 v34, v42, v43
	v_min_f32_e32 v35, 0, v35
	v_fmamk_f32 v34, v34, 0x3d800000, v33
	v_add_f32_e32 v38, 1.0, v40
	v_add_f32_e32 v36, -1.0, v38
	v_sub_f32_e32 v37, v36, v38
	v_add_f32_e32 v37, 1.0, v37
	v_sub_f32_e32 v36, v40, v36
	v_add_f32_e32 v39, v36, v37
	v_frexp_mant_f32_e32 v41, v38
	v_cvt_f64_f32_e32 v[36:37], v38
	v_frexp_exp_i32_f64_e32 v36, v[36:37]
	v_cmp_gt_f32_e32 vcc, s36, v41
	s_nop 1
	v_subbrev_co_u32_e32 v36, vcc, 0, v36, vcc
	v_sub_u32_e32 v37, 0, v36
	v_ldexp_f32 v38, v38, v37
	v_ldexp_f32 v37, v39, v37
	v_add_f32_e32 v39, -1.0, v38
	v_add_f32_e32 v43, 1.0, v38
	v_add_f32_e32 v41, 1.0, v39
	v_add_f32_e32 v44, -1.0, v43
	v_sub_f32_e32 v41, v38, v41
	v_sub_f32_e32 v38, v38, v44
	v_add_f32_e32 v41, v37, v41
	v_add_f32_e32 v37, v37, v38
	v_add_f32_e32 v38, v43, v37
	v_rcp_f32_e32 v44, v38
	v_add_f32_e32 v42, v39, v41
	v_sub_f32_e32 v39, v42, v39
	v_sub_f32_e32 v39, v41, v39
	v_sub_f32_e32 v41, v38, v43
	v_sub_f32_e32 v37, v37, v41
	v_mul_f32_e32 v41, v42, v44
	v_mul_f32_e32 v43, v38, v41
	v_fma_f32 v45, v41, v38, -v43
	v_fmac_f32_e32 v45, v41, v37
	v_add_f32_e32 v46, v43, v45
	v_sub_f32_e32 v47, v42, v46
	v_sub_f32_e32 v42, v42, v47
	v_sub_f32_e32 v43, v46, v43
	v_sub_f32_e32 v42, v42, v46
	v_add_f32_e32 v39, v39, v42
	v_sub_f32_e32 v42, v43, v45
	v_add_f32_e32 v39, v42, v39
	v_add_f32_e32 v42, v47, v39
	v_mul_f32_e32 v43, v44, v42
	v_mul_f32_e32 v45, v38, v43
	v_fma_f32 v38, v43, v38, -v45
	v_fmac_f32_e32 v38, v43, v37
	v_sub_f32_e32 v37, v47, v42
	v_add_f32_e32 v37, v39, v37
	v_add_f32_e32 v39, v45, v38
	v_sub_f32_e32 v46, v42, v39
	v_sub_f32_e32 v42, v42, v46
	v_sub_f32_e32 v45, v39, v45
	v_sub_f32_e32 v39, v42, v39
	v_add_f32_e32 v37, v37, v39
	v_sub_f32_e32 v38, v45, v38
	v_cvt_f32_i32_e32 v36, v36
	v_add_f32_e32 v37, v38, v37
	v_add_f32_e32 v38, v41, v43
	v_add_f32_e32 v37, v46, v37
	v_sub_f32_e32 v39, v38, v41
	v_mul_f32_e32 v37, v44, v37
	v_sub_f32_e32 v39, v43, v39
	v_add_f32_e32 v37, v39, v37
	v_mul_f32_e32 v43, 0x3f317218, v36
	v_add_f32_e32 v39, v38, v37
	v_fma_f32 v44, v36, s78, -v43
	v_mul_f32_e32 v41, v39, v39
	v_fmac_f32_e32 v44, 0xb102e308, v36
	v_sub_f32_e32 v36, v39, v38
	v_fmamk_f32 v42, v41, 0x3e9b6dac, v204
	v_sub_f32_e32 v36, v37, v36
	v_add_f32_e32 v37, v43, v44
	v_fmaak_f32 v42, v41, v42, 0x3f2aaada
	v_sub_f32_e32 v38, v37, v43
	v_ldexp_f32 v43, v39, 1
	v_mul_f32_e32 v39, v39, v41
	v_mul_f32_e32 v39, v39, v42
	v_add_f32_e32 v41, v43, v39
	v_sub_f32_e32 v42, v41, v43
	v_ldexp_f32 v36, v36, 1
	v_sub_f32_e32 v39, v39, v42
	v_add_f32_e32 v36, v36, v39
	v_add_f32_e32 v39, v41, v36
	v_sub_f32_e32 v41, v39, v41
	v_sub_f32_e32 v36, v36, v41
	v_add_f32_e32 v41, v37, v39
	v_sub_f32_e32 v42, v41, v37
	v_sub_f32_e32 v43, v41, v42
	v_sub_f32_e32 v38, v44, v38
	v_sub_f32_e32 v37, v37, v43
	v_sub_f32_e32 v39, v39, v42
	v_add_f32_e32 v37, v39, v37
	v_add_f32_e32 v39, v38, v36
	v_sub_f32_e32 v42, v39, v38
	v_sub_f32_e32 v43, v39, v42
	v_sub_f32_e32 v38, v38, v43
	v_sub_f32_e32 v36, v36, v42
	v_add_f32_e32 v37, v39, v37
	v_add_f32_e32 v36, v36, v38
	v_add_f32_e32 v38, v41, v37
	v_sub_f32_e32 v39, v38, v41
	v_sub_f32_e32 v37, v37, v39
	v_add_f32_e32 v36, v36, v37
	v_add_f32_e32 v36, v38, v36
	v_cmp_neq_f32_e32 vcc, s79, v40
	s_nop 1
	v_cndmask_b32_e32 v36, v211, v36, vcc
	v_cmp_ngt_f32_e32 vcc, -1.0, v40
	s_nop 1
	v_cndmask_b32_e32 v41, v212, v36, vcc
	ds_read_b128 v[36:39], v25 offset:27840
	v_cmp_neq_f32_e32 vcc, -1.0, v40
	s_nop 1
	v_cndmask_b32_e32 v41, v213, v41, vcc
	v_cmp_lt_f32_e64 vcc, |v40|, s2
	s_nop 1
	v_cndmask_b32_e32 v44, v41, v40, vcc
	ds_read_b128 v[40:43], v25 offset:27856
	s_waitcnt lgkmcnt(1)
	v_fma_f32 v45, v29, v36, v26
	v_fmac_f32_e32 v45, v30, v37
	v_fmac_f32_e32 v45, v31, v38
	v_fmac_f32_e32 v45, v32, v39
	ds_read_b128 v[36:39], v25 offset:27872
	s_waitcnt lgkmcnt(1)
	v_fmac_f32_e32 v45, v28, v40
	v_fmac_f32_e32 v45, v27, v41
	v_pk_mul_f32 v[40:41], v[12:13], v[42:43]
	v_sub_f32_e32 v35, v35, v44
	v_add_f32_e32 v40, v45, v40
	v_add_f32_e32 v45, v40, v41
	ds_read_b128 v[40:43], v25 offset:27888
	s_waitcnt lgkmcnt(1)
	v_pk_mul_f32 v[36:37], v[6:7], v[36:37]
	v_fmamk_f32 v35, v35, 0x3d800000, v34
	v_add_f32_e32 v36, v45, v36
	v_add_f32_e32 v45, v36, v37
	v_pk_mul_f32 v[36:37], v[4:5], v[38:39]
	s_nop 0
	v_add_f32_e32 v36, v45, v36
	v_add_f32_e32 v38, v36, v37
	s_waitcnt lgkmcnt(0)
	v_pk_mul_f32 v[36:37], v[8:9], v[40:41]
	s_nop 0
	v_add_f32_e32 v36, v38, v36
	v_add_f32_e32 v38, v36, v37
	v_pk_mul_f32 v[36:37], v[10:11], v[42:43]
	s_nop 0
	v_add_f32_e32 v36, v38, v36
	v_add_f32_e32 v36, v36, v37
	v_mul_f32_e64 v37, |v36|, s90
	v_exp_f32_e32 v40, v37
	v_min_f32_e32 v44, 0, v36
	v_add_f32_e32 v38, 1.0, v40
	v_add_f32_e32 v36, -1.0, v38
	v_sub_f32_e32 v37, v36, v38
	v_add_f32_e32 v37, 1.0, v37
	v_sub_f32_e32 v36, v40, v36
	v_add_f32_e32 v39, v36, v37
	v_frexp_mant_f32_e32 v41, v38
	v_cvt_f64_f32_e32 v[36:37], v38
	v_frexp_exp_i32_f64_e32 v36, v[36:37]
	v_cmp_gt_f32_e32 vcc, s36, v41
	s_nop 1
	v_subbrev_co_u32_e32 v36, vcc, 0, v36, vcc
	v_sub_u32_e32 v37, 0, v36
	v_ldexp_f32 v38, v38, v37
	v_ldexp_f32 v37, v39, v37
	v_add_f32_e32 v39, -1.0, v38
	v_add_f32_e32 v43, 1.0, v38
	v_add_f32_e32 v41, 1.0, v39
	v_add_f32_e32 v45, -1.0, v43
	v_sub_f32_e32 v41, v38, v41
	v_sub_f32_e32 v38, v38, v45
	v_add_f32_e32 v41, v37, v41
	v_add_f32_e32 v37, v37, v38
	v_add_f32_e32 v38, v43, v37
	v_rcp_f32_e32 v45, v38
	v_add_f32_e32 v42, v39, v41
	v_sub_f32_e32 v39, v42, v39
	v_sub_f32_e32 v39, v41, v39
	v_sub_f32_e32 v41, v38, v43
	v_sub_f32_e32 v37, v37, v41
	v_mul_f32_e32 v41, v42, v45
	v_mul_f32_e32 v43, v38, v41
	v_fma_f32 v46, v41, v38, -v43
	v_fmac_f32_e32 v46, v41, v37
	v_add_f32_e32 v47, v43, v46
	v_sub_f32_e32 v48, v42, v47
	v_sub_f32_e32 v42, v42, v48
	v_sub_f32_e32 v43, v47, v43
	v_sub_f32_e32 v42, v42, v47
	v_add_f32_e32 v39, v39, v42
	v_sub_f32_e32 v42, v43, v46
	v_add_f32_e32 v39, v42, v39
	v_add_f32_e32 v42, v48, v39
	v_mul_f32_e32 v43, v45, v42
	v_mul_f32_e32 v46, v38, v43
	v_fma_f32 v38, v43, v38, -v46
	v_fmac_f32_e32 v38, v43, v37
	v_sub_f32_e32 v37, v48, v42
	v_add_f32_e32 v37, v39, v37
	v_add_f32_e32 v39, v46, v38
	v_sub_f32_e32 v47, v42, v39
	v_sub_f32_e32 v42, v42, v47
	v_sub_f32_e32 v46, v39, v46
	v_sub_f32_e32 v39, v42, v39
	v_add_f32_e32 v37, v37, v39
	v_sub_f32_e32 v38, v46, v38
	v_cvt_f32_i32_e32 v36, v36
	v_add_f32_e32 v37, v38, v37
	v_add_f32_e32 v38, v41, v43
	v_add_f32_e32 v37, v47, v37
	v_sub_f32_e32 v39, v38, v41
	v_mul_f32_e32 v37, v45, v37
	v_sub_f32_e32 v39, v43, v39
	v_add_f32_e32 v37, v39, v37
	v_mul_f32_e32 v43, 0x3f317218, v36
	v_add_f32_e32 v39, v38, v37
	v_fma_f32 v45, v36, s78, -v43
	v_mul_f32_e32 v41, v39, v39
	v_fmac_f32_e32 v45, 0xb102e308, v36
	v_sub_f32_e32 v36, v39, v38
	v_fmamk_f32 v42, v41, 0x3e9b6dac, v204
	v_sub_f32_e32 v36, v37, v36
	v_add_f32_e32 v37, v43, v45
	v_fmaak_f32 v42, v41, v42, 0x3f2aaada
	v_sub_f32_e32 v38, v37, v43
	v_ldexp_f32 v43, v39, 1
	v_mul_f32_e32 v39, v39, v41
	v_mul_f32_e32 v39, v39, v42
	v_add_f32_e32 v41, v43, v39
	v_sub_f32_e32 v42, v41, v43
	v_ldexp_f32 v36, v36, 1
	v_sub_f32_e32 v39, v39, v42
	v_add_f32_e32 v36, v36, v39
	v_add_f32_e32 v39, v41, v36
	v_sub_f32_e32 v41, v39, v41
	v_sub_f32_e32 v36, v36, v41
	v_add_f32_e32 v41, v37, v39
	v_sub_f32_e32 v42, v41, v37
	v_sub_f32_e32 v43, v41, v42
	v_sub_f32_e32 v38, v45, v38
	v_sub_f32_e32 v37, v37, v43
	v_sub_f32_e32 v39, v39, v42
	v_add_f32_e32 v37, v39, v37
	v_add_f32_e32 v39, v38, v36
	v_sub_f32_e32 v42, v39, v38
	v_sub_f32_e32 v43, v39, v42
	v_sub_f32_e32 v38, v38, v43
	v_sub_f32_e32 v36, v36, v42
	v_add_f32_e32 v37, v39, v37
	v_add_f32_e32 v36, v36, v38
	v_add_f32_e32 v38, v41, v37
	v_sub_f32_e32 v39, v38, v41
	v_sub_f32_e32 v37, v37, v39
	v_add_f32_e32 v36, v36, v37
	v_add_f32_e32 v36, v38, v36
	v_cmp_neq_f32_e32 vcc, s79, v40
	s_nop 1
	v_cndmask_b32_e32 v36, v211, v36, vcc
	v_cmp_ngt_f32_e32 vcc, -1.0, v40
	s_nop 1
	v_cndmask_b32_e32 v41, v212, v36, vcc
	ds_read_b128 v[36:39], v25 offset:27904
	v_cmp_neq_f32_e32 vcc, -1.0, v40
	s_nop 1
	v_cndmask_b32_e32 v41, v213, v41, vcc
	v_cmp_lt_f32_e64 vcc, |v40|, s2
	s_nop 1
	v_cndmask_b32_e32 v45, v41, v40, vcc
	ds_read_b128 v[40:43], v25 offset:27920
	s_waitcnt lgkmcnt(1)
	v_fma_f32 v46, v29, v36, v26
	v_fmac_f32_e32 v46, v30, v37
	v_fmac_f32_e32 v46, v31, v38
	v_fmac_f32_e32 v46, v32, v39
	ds_read_b128 v[36:39], v25 offset:27936
	s_waitcnt lgkmcnt(1)
	v_fmac_f32_e32 v46, v28, v40
	v_fmac_f32_e32 v46, v27, v41
	v_pk_mul_f32 v[40:41], v[12:13], v[42:43]
	s_nop 0
	v_add_f32_e32 v40, v46, v40
	v_add_f32_e32 v46, v40, v41
	ds_read_b128 v[40:43], v25 offset:27952
	s_waitcnt lgkmcnt(1)
	v_pk_mul_f32 v[36:37], v[6:7], v[36:37]
	s_nop 0
	v_add_f32_e32 v36, v46, v36
	v_add_f32_e32 v46, v36, v37
	v_pk_mul_f32 v[36:37], v[4:5], v[38:39]
	s_nop 0
	v_add_f32_e32 v36, v46, v36
	v_add_f32_e32 v38, v36, v37
	s_waitcnt lgkmcnt(0)
	v_pk_mul_f32 v[36:37], v[8:9], v[40:41]
	s_nop 0
	v_add_f32_e32 v36, v38, v36
	v_add_f32_e32 v38, v36, v37
	v_pk_mul_f32 v[36:37], v[10:11], v[42:43]
	s_nop 0
	v_add_f32_e32 v36, v38, v36
	v_add_f32_e32 v37, v36, v37
	v_mul_f32_e64 v36, |v37|, s90
	v_exp_f32_e32 v42, v36
	v_sub_f32_e32 v36, v44, v45
	v_min_f32_e32 v37, 0, v37
	v_fmamk_f32 v36, v36, 0x3d800000, v35
	v_add_f32_e32 v40, 1.0, v42
	v_add_f32_e32 v38, -1.0, v40
	v_sub_f32_e32 v39, v38, v40
	v_add_f32_e32 v39, 1.0, v39
	v_sub_f32_e32 v38, v42, v38
	v_add_f32_e32 v41, v38, v39
	v_frexp_mant_f32_e32 v43, v40
	v_cvt_f64_f32_e32 v[38:39], v40
	v_frexp_exp_i32_f64_e32 v38, v[38:39]
	v_cmp_gt_f32_e32 vcc, s36, v43
	s_nop 1
	v_subbrev_co_u32_e32 v38, vcc, 0, v38, vcc
	v_sub_u32_e32 v39, 0, v38
	v_ldexp_f32 v40, v40, v39
	v_ldexp_f32 v39, v41, v39
	v_add_f32_e32 v41, -1.0, v40
	v_add_f32_e32 v45, 1.0, v40
	v_add_f32_e32 v43, 1.0, v41
	v_add_f32_e32 v46, -1.0, v45
	v_sub_f32_e32 v43, v40, v43
	v_sub_f32_e32 v40, v40, v46
	v_add_f32_e32 v43, v39, v43
	v_add_f32_e32 v39, v39, v40
	v_add_f32_e32 v40, v45, v39
	v_rcp_f32_e32 v46, v40
	v_add_f32_e32 v44, v41, v43
	v_sub_f32_e32 v41, v44, v41
	v_sub_f32_e32 v41, v43, v41
	v_sub_f32_e32 v43, v40, v45
	v_sub_f32_e32 v39, v39, v43
	v_mul_f32_e32 v43, v44, v46
	v_mul_f32_e32 v45, v40, v43
	v_fma_f32 v47, v43, v40, -v45
	v_fmac_f32_e32 v47, v43, v39
	v_add_f32_e32 v48, v45, v47
	v_sub_f32_e32 v49, v44, v48
	v_sub_f32_e32 v44, v44, v49
	v_sub_f32_e32 v45, v48, v45
	v_sub_f32_e32 v44, v44, v48
	v_add_f32_e32 v41, v41, v44
	v_sub_f32_e32 v44, v45, v47
	v_add_f32_e32 v41, v44, v41
	v_add_f32_e32 v44, v49, v41
	v_mul_f32_e32 v45, v46, v44
	v_mul_f32_e32 v47, v40, v45
	v_fma_f32 v40, v45, v40, -v47
	v_fmac_f32_e32 v40, v45, v39
	v_sub_f32_e32 v39, v49, v44
	v_add_f32_e32 v39, v41, v39
	v_add_f32_e32 v41, v47, v40
	v_sub_f32_e32 v48, v44, v41
	v_sub_f32_e32 v44, v44, v48
	v_sub_f32_e32 v47, v41, v47
	v_sub_f32_e32 v41, v44, v41
	v_add_f32_e32 v39, v39, v41
	v_sub_f32_e32 v40, v47, v40
	v_cvt_f32_i32_e32 v38, v38
	v_add_f32_e32 v39, v40, v39
	v_add_f32_e32 v40, v43, v45
	v_add_f32_e32 v39, v48, v39
	v_sub_f32_e32 v41, v40, v43
	v_mul_f32_e32 v39, v46, v39
	v_sub_f32_e32 v41, v45, v41
	v_add_f32_e32 v39, v41, v39
	v_mul_f32_e32 v45, 0x3f317218, v38
	v_add_f32_e32 v41, v40, v39
	v_fma_f32 v46, v38, s78, -v45
	v_mul_f32_e32 v43, v41, v41
	v_fmac_f32_e32 v46, 0xb102e308, v38
	v_sub_f32_e32 v38, v41, v40
	v_fmamk_f32 v44, v43, 0x3e9b6dac, v204
	v_sub_f32_e32 v38, v39, v38
	v_add_f32_e32 v39, v45, v46
	v_fmaak_f32 v44, v43, v44, 0x3f2aaada
	v_sub_f32_e32 v40, v39, v45
	v_ldexp_f32 v45, v41, 1
	v_mul_f32_e32 v41, v41, v43
	v_mul_f32_e32 v41, v41, v44
	v_add_f32_e32 v43, v45, v41
	v_sub_f32_e32 v44, v43, v45
	v_ldexp_f32 v38, v38, 1
	v_sub_f32_e32 v41, v41, v44
	v_add_f32_e32 v38, v38, v41
	v_add_f32_e32 v41, v43, v38
	v_sub_f32_e32 v43, v41, v43
	v_sub_f32_e32 v38, v38, v43
	v_add_f32_e32 v43, v39, v41
	v_sub_f32_e32 v44, v43, v39
	v_sub_f32_e32 v45, v43, v44
	v_sub_f32_e32 v40, v46, v40
	v_sub_f32_e32 v39, v39, v45
	v_sub_f32_e32 v41, v41, v44
	v_add_f32_e32 v39, v41, v39
	v_add_f32_e32 v41, v40, v38
	v_sub_f32_e32 v44, v41, v40
	v_sub_f32_e32 v45, v41, v44
	v_sub_f32_e32 v40, v40, v45
	v_sub_f32_e32 v38, v38, v44
	v_add_f32_e32 v39, v41, v39
	v_add_f32_e32 v38, v38, v40
	v_add_f32_e32 v40, v43, v39
	v_sub_f32_e32 v41, v40, v43
	v_sub_f32_e32 v39, v39, v41
	v_add_f32_e32 v38, v38, v39
	v_add_f32_e32 v38, v40, v38
	v_cmp_neq_f32_e32 vcc, s79, v42
	s_nop 1
	v_cndmask_b32_e32 v38, v211, v38, vcc
	v_cmp_ngt_f32_e32 vcc, -1.0, v42
	s_nop 1
	v_cndmask_b32_e32 v43, v212, v38, vcc
	ds_read_b128 v[38:41], v25 offset:27968
	v_cmp_neq_f32_e32 vcc, -1.0, v42
	s_nop 1
	v_cndmask_b32_e32 v43, v213, v43, vcc
	v_cmp_lt_f32_e64 vcc, |v42|, s2
	s_nop 1
	v_cndmask_b32_e32 v46, v43, v42, vcc
	ds_read_b128 v[42:45], v25 offset:27984
	s_waitcnt lgkmcnt(1)
	v_fma_f32 v47, v29, v38, v26
	v_fmac_f32_e32 v47, v30, v39
	v_fmac_f32_e32 v47, v31, v40
	v_fmac_f32_e32 v47, v32, v41
	ds_read_b128 v[38:41], v25 offset:28000
	s_waitcnt lgkmcnt(1)
	v_fmac_f32_e32 v47, v28, v42
	v_fmac_f32_e32 v47, v27, v43
	v_pk_mul_f32 v[42:43], v[12:13], v[44:45]
	v_sub_f32_e32 v37, v37, v46
	v_add_f32_e32 v42, v47, v42
	v_add_f32_e32 v47, v42, v43
	ds_read_b128 v[42:45], v25 offset:28016
	s_waitcnt lgkmcnt(1)
	v_pk_mul_f32 v[38:39], v[6:7], v[38:39]
	v_fmamk_f32 v37, v37, 0x3d800000, v36
	v_add_f32_e32 v38, v47, v38
	v_add_f32_e32 v47, v38, v39
	v_pk_mul_f32 v[38:39], v[4:5], v[40:41]
	s_nop 0
	v_add_f32_e32 v38, v47, v38
	v_add_f32_e32 v40, v38, v39
	s_waitcnt lgkmcnt(0)
	v_pk_mul_f32 v[38:39], v[8:9], v[42:43]
	s_nop 0
	v_add_f32_e32 v38, v40, v38
	v_add_f32_e32 v40, v38, v39
	v_pk_mul_f32 v[38:39], v[10:11], v[44:45]
	s_nop 0
	v_add_f32_e32 v38, v40, v38
	v_add_f32_e32 v38, v38, v39
	v_mul_f32_e64 v39, |v38|, s90
	v_exp_f32_e32 v52, v39
	v_min_f32_e32 v53, 0, v38
	v_add_f32_e32 v40, 1.0, v52
	v_add_f32_e32 v38, -1.0, v40
	v_sub_f32_e32 v39, v38, v40
	v_add_f32_e32 v39, 1.0, v39
	v_sub_f32_e32 v38, v52, v38
	v_add_f32_e32 v41, v38, v39
	v_frexp_mant_f32_e32 v42, v40
	v_cvt_f64_f32_e32 v[38:39], v40
	v_frexp_exp_i32_f64_e32 v38, v[38:39]
	v_cmp_gt_f32_e32 vcc, s36, v42
	s_nop 1
	v_subbrev_co_u32_e32 v46, vcc, 0, v38, vcc
	v_sub_u32_e32 v38, 0, v46
	v_ldexp_f32 v39, v40, v38
	v_add_f32_e32 v40, -1.0, v39
	v_add_f32_e32 v42, 1.0, v39
	v_ldexp_f32 v38, v41, v38
	v_add_f32_e32 v41, 1.0, v40
	v_add_f32_e32 v43, -1.0, v42
	v_sub_f32_e32 v41, v39, v41
	v_sub_f32_e32 v39, v39, v43
	v_add_f32_e32 v41, v38, v41
	v_add_f32_e32 v38, v38, v39
	v_add_f32_e32 v47, v42, v38
	v_rcp_f32_e32 v49, v47
	v_sub_f32_e32 v39, v47, v42
	v_sub_f32_e32 v48, v38, v39
	v_add_f32_e32 v39, v40, v41
	v_mul_f32_e32 v51, v39, v49
	v_sub_f32_e32 v38, v39, v40
	v_mul_f32_e32 v40, v47, v51
	v_fma_f32 v42, v51, v47, -v40
	v_fmac_f32_e32 v42, v51, v48
	v_sub_f32_e32 v50, v41, v38
	v_add_f32_e32 v38, v40, v42
	v_sub_f32_e32 v41, v39, v38
	v_pk_add_f32 v[44:45], v[38:39], v[40:41] neg_lo:[0,1] neg_hi:[0,1]
	v_mov_b32_e32 v43, v38
	v_pk_add_f32 v[38:39], v[44:45], v[42:43] neg_lo:[0,1] neg_hi:[0,1]
	v_cmp_neq_f32_e32 vcc, s79, v52
	v_add_f32_e32 v39, v50, v39
	v_add_f32_e32 v38, v38, v39
	v_add_f32_e32 v39, v41, v38
	v_mul_f32_e32 v50, v49, v39
	v_mul_f32_e32 v40, v47, v50
	v_fma_f32 v42, v50, v47, -v40
	v_fmac_f32_e32 v42, v50, v48
	v_sub_f32_e32 v41, v41, v39
	v_add_f32_e32 v47, v38, v41
	v_add_f32_e32 v38, v40, v42
	v_sub_f32_e32 v41, v39, v38
	v_pk_add_f32 v[44:45], v[38:39], v[40:41] neg_lo:[0,1] neg_hi:[0,1]
	v_mov_b32_e32 v43, v38
	v_pk_add_f32 v[38:39], v[44:45], v[42:43] neg_lo:[0,1] neg_hi:[0,1]
	s_nop 0
	v_add_f32_e32 v39, v47, v39
	v_add_f32_e32 v38, v38, v39
	v_add_f32_e32 v39, v51, v50
	v_add_f32_e32 v38, v41, v38
	v_sub_f32_e32 v40, v39, v51
	v_mul_f32_e32 v38, v49, v38
	v_sub_f32_e32 v40, v50, v40
	v_add_f32_e32 v40, v40, v38
	v_add_f32_e32 v42, v39, v40
	v_mul_f32_e32 v43, v42, v42
	v_fmamk_f32 v38, v43, 0x3e9b6dac, v204
	v_fmaak_f32 v175, v43, v38, 0x3f2aaada
	v_cvt_f32_i32_e32 v38, v46
	v_sub_f32_e32 v39, v42, v39
	v_sub_f32_e32 v39, v40, v39
	v_ldexp_f32 v44, v39, 1
	v_mul_f32_e32 v39, v42, v43
	v_ldexp_f32 v41, v42, 1
	v_pk_mul_f32 v[42:43], v[38:39], v[174:175]
	s_nop 0
	v_fma_f32 v40, v38, s78, -v42
	v_fmac_f32_e32 v40, 0xb102e308, v38
	v_pk_add_f32 v[38:39], v[42:43], v[40:41]
	s_nop 0
	v_sub_f32_e32 v41, v39, v41
	v_sub_f32_e32 v41, v43, v41
	v_add_f32_e32 v45, v44, v41
	v_mov_b32_e32 v44, v42
	v_pk_add_f32 v[42:43], v[38:39], v[42:43] neg_lo:[0,1] neg_hi:[0,1]
	v_pk_add_f32 v[46:47], v[38:39], v[44:45]
	v_mov_b32_e32 v41, v38
	v_mov_b32_e32 v43, v47
	v_pk_add_f32 v[48:49], v[40:41], v[42:43] neg_lo:[0,1] neg_hi:[0,1]
	v_pk_add_f32 v[40:41], v[40:41], v[42:43]
	v_mov_b32_e32 v44, v45
	v_pk_add_f32 v[42:43], v[40:41], v[38:39] op_sel:[1,0] op_sel_hi:[0,1] neg_lo:[0,1] neg_hi:[0,1]
	v_pk_add_f32 v[50:51], v[46:47], v[42:43] op_sel_hi:[1,0] neg_lo:[0,1] neg_hi:[0,1]
	v_mov_b32_e32 v46, v47
	v_mov_b32_e32 v47, v41
	v_pk_mov_b32 v[42:43], v[38:39], v[42:43] op_sel:[1,0]
	v_mov_b32_e32 v45, v38
	v_pk_add_f32 v[42:43], v[46:47], v[42:43] neg_lo:[0,1] neg_hi:[0,1]
	v_mov_b32_e32 v50, v48
	v_pk_add_f32 v[38:39], v[44:45], v[42:43] neg_lo:[0,1] neg_hi:[0,1]
	v_mov_b32_e32 v49, v41
	v_pk_add_f32 v[42:43], v[50:51], v[38:39]
	s_nop 0
	v_pk_add_f32 v[44:45], v[42:43], v[42:43] op_sel:[0,1] op_sel_hi:[1,0]
	s_nop 0
	v_pk_add_f32 v[40:41], v[40:41], v[44:45] op_sel:[1,0] op_sel_hi:[0,1]
	v_mov_b32_e32 v43, v40
	v_pk_add_f32 v[46:47], v[42:43], v[48:49] neg_lo:[0,1] neg_hi:[0,1]
	v_mov_b32_e32 v39, v44
	v_sub_f32_e32 v41, v42, v46
	v_pk_add_f32 v[38:39], v[38:39], v[46:47] neg_lo:[0,1] neg_hi:[0,1]
	v_sub_f32_e32 v41, v48, v41
	v_add_f32_e32 v38, v38, v41
	v_add_f32_e32 v38, v38, v39
	v_add_f32_e32 v38, v40, v38
	v_cndmask_b32_e32 v38, v211, v38, vcc
	v_cmp_ngt_f32_e32 vcc, -1.0, v52
	s_nop 1
	v_cndmask_b32_e32 v42, v212, v38, vcc
	ds_read_b128 v[38:41], v25 offset:28032
	v_cmp_neq_f32_e32 vcc, -1.0, v52
	s_nop 1
	v_cndmask_b32_e32 v42, v213, v42, vcc
	v_cmp_lt_f32_e64 vcc, |v52|, s2
	s_nop 1
	v_cndmask_b32_e32 v46, v42, v52, vcc
	ds_read_b128 v[42:45], v25 offset:28048
	s_waitcnt lgkmcnt(1)
	v_fma_f32 v47, v29, v38, v26
	v_fmac_f32_e32 v47, v30, v39
	v_fmac_f32_e32 v47, v31, v40
	v_fmac_f32_e32 v47, v32, v41
	ds_read_b128 v[38:41], v25 offset:28064
	s_waitcnt lgkmcnt(1)
	v_fmac_f32_e32 v47, v28, v42
	v_fmac_f32_e32 v47, v27, v43
	v_pk_mul_f32 v[42:43], v[12:13], v[44:45]
	s_nop 0
	v_add_f32_e32 v42, v47, v42
	v_add_f32_e32 v47, v42, v43
	ds_read_b128 v[42:45], v25 offset:28080
	s_waitcnt lgkmcnt(1)
	v_pk_mul_f32 v[38:39], v[6:7], v[38:39]
	s_nop 0
	v_add_f32_e32 v38, v47, v38
	v_add_f32_e32 v47, v38, v39
	v_pk_mul_f32 v[38:39], v[4:5], v[40:41]
	s_nop 0
	v_add_f32_e32 v38, v47, v38
	v_add_f32_e32 v40, v38, v39
	s_waitcnt lgkmcnt(0)
	v_pk_mul_f32 v[38:39], v[8:9], v[42:43]
	s_nop 0
	v_add_f32_e32 v38, v40, v38
	v_add_f32_e32 v40, v38, v39
	v_pk_mul_f32 v[38:39], v[10:11], v[44:45]
	s_nop 0
	v_add_f32_e32 v38, v40, v38
	v_add_f32_e32 v38, v38, v39
	v_mul_f32_e64 v39, |v38|, s90
	v_exp_f32_e32 v52, v39
	v_sub_f32_e32 v39, v53, v46
	v_min_f32_e32 v54, 0, v38
	v_fmamk_f32 v53, v39, 0x3d800000, v37
	v_add_f32_e32 v40, 1.0, v52
	v_add_f32_e32 v38, -1.0, v40
	v_sub_f32_e32 v39, v38, v40
	v_add_f32_e32 v39, 1.0, v39
	v_sub_f32_e32 v38, v52, v38
	v_add_f32_e32 v41, v38, v39
	v_frexp_mant_f32_e32 v42, v40
	v_cvt_f64_f32_e32 v[38:39], v40
	v_frexp_exp_i32_f64_e32 v38, v[38:39]
	v_cmp_gt_f32_e32 vcc, s36, v42
	s_nop 1
	v_subbrev_co_u32_e32 v46, vcc, 0, v38, vcc
	v_sub_u32_e32 v38, 0, v46
	v_ldexp_f32 v39, v40, v38
	v_add_f32_e32 v40, -1.0, v39
	v_add_f32_e32 v42, 1.0, v39
	v_ldexp_f32 v38, v41, v38
	v_add_f32_e32 v41, 1.0, v40
	v_add_f32_e32 v43, -1.0, v42
	v_sub_f32_e32 v41, v39, v41
	v_sub_f32_e32 v39, v39, v43
	v_add_f32_e32 v41, v38, v41
	v_add_f32_e32 v38, v38, v39
	v_add_f32_e32 v47, v42, v38
	v_rcp_f32_e32 v49, v47
	v_sub_f32_e32 v39, v47, v42
	v_sub_f32_e32 v48, v38, v39
	v_add_f32_e32 v39, v40, v41
	v_mul_f32_e32 v51, v39, v49
	v_sub_f32_e32 v38, v39, v40
	v_mul_f32_e32 v40, v47, v51
	v_fma_f32 v42, v51, v47, -v40
	v_fmac_f32_e32 v42, v51, v48
	v_sub_f32_e32 v50, v41, v38
	v_add_f32_e32 v38, v40, v42
	v_sub_f32_e32 v41, v39, v38
	v_pk_add_f32 v[44:45], v[38:39], v[40:41] neg_lo:[0,1] neg_hi:[0,1]
	v_mov_b32_e32 v43, v38
	v_pk_add_f32 v[38:39], v[44:45], v[42:43] neg_lo:[0,1] neg_hi:[0,1]
	v_cmp_neq_f32_e32 vcc, s79, v52
	v_add_f32_e32 v39, v50, v39
	v_add_f32_e32 v38, v38, v39
	v_add_f32_e32 v39, v41, v38
	v_mul_f32_e32 v50, v49, v39
	v_mul_f32_e32 v40, v47, v50
	v_fma_f32 v42, v50, v47, -v40
	v_fmac_f32_e32 v42, v50, v48
	v_sub_f32_e32 v41, v41, v39
	v_add_f32_e32 v47, v38, v41
	v_add_f32_e32 v38, v40, v42
	v_sub_f32_e32 v41, v39, v38
	v_pk_add_f32 v[44:45], v[38:39], v[40:41] neg_lo:[0,1] neg_hi:[0,1]
	v_mov_b32_e32 v43, v38
	v_pk_add_f32 v[38:39], v[44:45], v[42:43] neg_lo:[0,1] neg_hi:[0,1]
	s_nop 0
	v_add_f32_e32 v39, v47, v39
	v_add_f32_e32 v38, v38, v39
	v_add_f32_e32 v39, v51, v50
	v_add_f32_e32 v38, v41, v38
	v_sub_f32_e32 v40, v39, v51
	v_mul_f32_e32 v38, v49, v38
	v_sub_f32_e32 v40, v50, v40
	v_add_f32_e32 v40, v40, v38
	v_add_f32_e32 v42, v39, v40
	v_mul_f32_e32 v43, v42, v42
	v_fmamk_f32 v38, v43, 0x3e9b6dac, v204
	v_fmaak_f32 v175, v43, v38, 0x3f2aaada
	v_cvt_f32_i32_e32 v38, v46
	v_sub_f32_e32 v39, v42, v39
	v_sub_f32_e32 v39, v40, v39
	v_ldexp_f32 v44, v39, 1
	v_mul_f32_e32 v39, v42, v43
	v_ldexp_f32 v41, v42, 1
	v_pk_mul_f32 v[42:43], v[38:39], v[174:175]
	s_nop 0
	v_fma_f32 v40, v38, s78, -v42
	v_fmac_f32_e32 v40, 0xb102e308, v38
	v_pk_add_f32 v[38:39], v[42:43], v[40:41]
	s_nop 0
	v_sub_f32_e32 v41, v39, v41
	v_sub_f32_e32 v41, v43, v41
	v_add_f32_e32 v45, v44, v41
	v_mov_b32_e32 v44, v42
	v_pk_add_f32 v[42:43], v[38:39], v[42:43] neg_lo:[0,1] neg_hi:[0,1]
	v_pk_add_f32 v[46:47], v[38:39], v[44:45]
	v_mov_b32_e32 v41, v38
	v_mov_b32_e32 v43, v47
	v_pk_add_f32 v[48:49], v[40:41], v[42:43] neg_lo:[0,1] neg_hi:[0,1]
	v_pk_add_f32 v[40:41], v[40:41], v[42:43]
	v_mov_b32_e32 v44, v45
	v_pk_add_f32 v[42:43], v[40:41], v[38:39] op_sel:[1,0] op_sel_hi:[0,1] neg_lo:[0,1] neg_hi:[0,1]
	v_pk_add_f32 v[50:51], v[46:47], v[42:43] op_sel_hi:[1,0] neg_lo:[0,1] neg_hi:[0,1]
	v_mov_b32_e32 v46, v47
	v_mov_b32_e32 v47, v41
	v_pk_mov_b32 v[42:43], v[38:39], v[42:43] op_sel:[1,0]
	v_mov_b32_e32 v45, v38
	v_pk_add_f32 v[42:43], v[46:47], v[42:43] neg_lo:[0,1] neg_hi:[0,1]
	v_mov_b32_e32 v50, v48
	v_pk_add_f32 v[38:39], v[44:45], v[42:43] neg_lo:[0,1] neg_hi:[0,1]
	v_mov_b32_e32 v49, v41
	v_pk_add_f32 v[42:43], v[50:51], v[38:39]
	s_nop 0
	v_pk_add_f32 v[44:45], v[42:43], v[42:43] op_sel:[0,1] op_sel_hi:[1,0]
	s_nop 0
	v_pk_add_f32 v[40:41], v[40:41], v[44:45] op_sel:[1,0] op_sel_hi:[0,1]
	v_mov_b32_e32 v43, v40
	v_pk_add_f32 v[46:47], v[42:43], v[48:49] neg_lo:[0,1] neg_hi:[0,1]
	v_mov_b32_e32 v39, v44
	v_sub_f32_e32 v41, v42, v46
	v_pk_add_f32 v[38:39], v[38:39], v[46:47] neg_lo:[0,1] neg_hi:[0,1]
	v_sub_f32_e32 v41, v48, v41
	v_add_f32_e32 v38, v38, v41
	v_add_f32_e32 v38, v38, v39
	v_add_f32_e32 v38, v40, v38
	v_cndmask_b32_e32 v38, v211, v38, vcc
	v_cmp_ngt_f32_e32 vcc, -1.0, v52
	s_nop 1
	v_cndmask_b32_e32 v42, v212, v38, vcc
	ds_read_b128 v[38:41], v25 offset:28096
	v_cmp_neq_f32_e32 vcc, -1.0, v52
	s_nop 1
	v_cndmask_b32_e32 v42, v213, v42, vcc
	v_cmp_lt_f32_e64 vcc, |v52|, s2
	s_nop 1
	v_cndmask_b32_e32 v46, v42, v52, vcc
	ds_read_b128 v[42:45], v25 offset:28112
	s_waitcnt lgkmcnt(1)
	v_fmac_f32_e32 v26, v29, v38
	v_fmac_f32_e32 v26, v30, v39
	v_fmac_f32_e32 v26, v31, v40
	v_fmac_f32_e32 v26, v32, v41
	s_waitcnt lgkmcnt(0)
	v_fmac_f32_e32 v26, v28, v42
	ds_read_b128 v[28:31], v25 offset:28128
	ds_read_b128 v[38:41], v25 offset:28144
	v_fmac_f32_e32 v26, v27, v43
	v_pk_mul_f32 v[12:13], v[12:13], v[44:45]
	s_waitcnt lgkmcnt(1)
	v_pk_mul_f32 v[6:7], v[6:7], v[28:29]
	v_add_f32_e32 v12, v26, v12
	v_add_f32_e32 v12, v12, v13
	v_add_f32_e32 v6, v12, v6
	v_add_f32_e32 v6, v6, v7
	v_pk_mul_f32 v[4:5], v[4:5], v[30:31]
	s_nop 0
	v_add_f32_e32 v4, v6, v4
	v_add_f32_e32 v6, v4, v5
	s_waitcnt lgkmcnt(0)
	v_pk_mul_f32 v[4:5], v[8:9], v[38:39]
	s_nop 0
	v_add_f32_e32 v4, v6, v4
	v_add_f32_e32 v6, v4, v5
	v_pk_mul_f32 v[4:5], v[10:11], v[40:41]
	s_nop 0
	v_add_f32_e32 v4, v6, v4
	v_add_f32_e32 v4, v4, v5
	v_mul_f32_e64 v5, |v4|, s90
	v_exp_f32_e32 v25, v5
	v_sub_f32_e32 v5, v54, v46
	v_min_f32_e32 v31, 0, v4
	v_fmamk_f32 v30, v5, 0x3d800000, v53
	v_add_f32_e32 v6, 1.0, v25
	v_add_f32_e32 v4, -1.0, v6
	v_sub_f32_e32 v5, v4, v6
	v_add_f32_e32 v5, 1.0, v5
	v_sub_f32_e32 v4, v25, v4
	v_add_f32_e32 v7, v4, v5
	v_frexp_mant_f32_e32 v8, v6
	v_cvt_f64_f32_e32 v[4:5], v6
	v_frexp_exp_i32_f64_e32 v4, v[4:5]
	v_cmp_gt_f32_e32 vcc, s36, v8
	s_nop 1
	v_subbrev_co_u32_e32 v12, vcc, 0, v4, vcc
	v_sub_u32_e32 v4, 0, v12
	v_ldexp_f32 v5, v6, v4
	v_add_f32_e32 v6, -1.0, v5
	v_add_f32_e32 v8, 1.0, v5
	v_ldexp_f32 v4, v7, v4
	v_add_f32_e32 v7, 1.0, v6
	v_add_f32_e32 v9, -1.0, v8
	v_sub_f32_e32 v7, v5, v7
	v_sub_f32_e32 v5, v5, v9
	v_add_f32_e32 v7, v4, v7
	v_add_f32_e32 v4, v4, v5
	v_add_f32_e32 v13, v8, v4
	v_rcp_f32_e32 v27, v13
	v_sub_f32_e32 v5, v13, v8
	v_sub_f32_e32 v26, v4, v5
	v_add_f32_e32 v5, v6, v7
	v_mul_f32_e32 v29, v5, v27
	v_sub_f32_e32 v4, v5, v6
	v_mul_f32_e32 v6, v13, v29
	v_fma_f32 v8, v29, v13, -v6
	v_fmac_f32_e32 v8, v29, v26
	v_sub_f32_e32 v28, v7, v4
	v_add_f32_e32 v4, v6, v8
	v_sub_f32_e32 v7, v5, v4
	v_pk_add_f32 v[10:11], v[4:5], v[6:7] neg_lo:[0,1] neg_hi:[0,1]
	v_mov_b32_e32 v9, v4
	v_pk_add_f32 v[4:5], v[10:11], v[8:9] neg_lo:[0,1] neg_hi:[0,1]
	v_cmp_neq_f32_e32 vcc, s79, v25
	v_add_f32_e32 v5, v28, v5
	v_add_f32_e32 v4, v4, v5
	v_add_f32_e32 v5, v7, v4
	v_mul_f32_e32 v28, v27, v5
	v_mul_f32_e32 v6, v13, v28
	v_fma_f32 v8, v28, v13, -v6
	v_fmac_f32_e32 v8, v28, v26
	v_sub_f32_e32 v7, v7, v5
	v_add_f32_e32 v13, v4, v7
	v_add_f32_e32 v4, v6, v8
	v_sub_f32_e32 v7, v5, v4
	v_pk_add_f32 v[10:11], v[4:5], v[6:7] neg_lo:[0,1] neg_hi:[0,1]
	v_mov_b32_e32 v9, v4
	v_pk_add_f32 v[4:5], v[10:11], v[8:9] neg_lo:[0,1] neg_hi:[0,1]
	s_nop 0
	v_add_f32_e32 v5, v13, v5
	v_add_f32_e32 v4, v4, v5
	v_add_f32_e32 v5, v29, v28
	v_add_f32_e32 v4, v7, v4
	v_sub_f32_e32 v6, v5, v29
	v_mul_f32_e32 v4, v27, v4
	v_sub_f32_e32 v6, v28, v6
	v_add_f32_e32 v6, v6, v4
	v_add_f32_e32 v8, v5, v6
	v_mul_f32_e32 v9, v8, v8
	v_fmamk_f32 v4, v9, 0x3e9b6dac, v204
	v_fmaak_f32 v175, v9, v4, 0x3f2aaada
	v_cvt_f32_i32_e32 v4, v12
	v_sub_f32_e32 v5, v8, v5
	v_sub_f32_e32 v5, v6, v5
	v_ldexp_f32 v10, v5, 1
	v_mul_f32_e32 v5, v8, v9
	v_ldexp_f32 v7, v8, 1
	v_pk_mul_f32 v[8:9], v[4:5], v[174:175]
	s_nop 0
	v_fma_f32 v6, v4, s78, -v8
	v_fmac_f32_e32 v6, 0xb102e308, v4
	v_pk_add_f32 v[4:5], v[8:9], v[6:7]
	s_nop 0
	v_sub_f32_e32 v7, v5, v7
	v_sub_f32_e32 v7, v9, v7
	v_add_f32_e32 v11, v10, v7
	v_mov_b32_e32 v10, v8
	v_pk_add_f32 v[8:9], v[4:5], v[8:9] neg_lo:[0,1] neg_hi:[0,1]
	v_pk_add_f32 v[12:13], v[4:5], v[10:11]
	v_mov_b32_e32 v7, v4
	v_mov_b32_e32 v9, v13
	v_pk_add_f32 v[26:27], v[6:7], v[8:9] neg_lo:[0,1] neg_hi:[0,1]
	v_pk_add_f32 v[6:7], v[6:7], v[8:9]
	v_mov_b32_e32 v10, v11
	v_pk_add_f32 v[8:9], v[6:7], v[4:5] op_sel:[1,0] op_sel_hi:[0,1] neg_lo:[0,1] neg_hi:[0,1]
	v_pk_add_f32 v[28:29], v[12:13], v[8:9] op_sel_hi:[1,0] neg_lo:[0,1] neg_hi:[0,1]
	v_mov_b32_e32 v12, v13
	v_mov_b32_e32 v13, v7
	v_pk_mov_b32 v[8:9], v[4:5], v[8:9] op_sel:[1,0]
	v_mov_b32_e32 v11, v4
	v_pk_add_f32 v[8:9], v[12:13], v[8:9] neg_lo:[0,1] neg_hi:[0,1]
	v_mov_b32_e32 v28, v26
	v_pk_add_f32 v[4:5], v[10:11], v[8:9] neg_lo:[0,1] neg_hi:[0,1]
	v_mov_b32_e32 v27, v7
	v_pk_add_f32 v[8:9], v[28:29], v[4:5]
	s_nop 0
	v_pk_add_f32 v[10:11], v[8:9], v[8:9] op_sel:[0,1] op_sel_hi:[1,0]
	s_nop 0
	v_pk_add_f32 v[6:7], v[6:7], v[10:11] op_sel:[1,0] op_sel_hi:[0,1]
	v_mov_b32_e32 v9, v6
	v_pk_add_f32 v[12:13], v[8:9], v[26:27] neg_lo:[0,1] neg_hi:[0,1]
	v_mov_b32_e32 v5, v10
	v_sub_f32_e32 v7, v8, v12
	v_pk_add_f32 v[4:5], v[4:5], v[12:13] neg_lo:[0,1] neg_hi:[0,1]
	v_sub_f32_e32 v7, v26, v7
	v_add_f32_e32 v4, v4, v7
	v_add_f32_e32 v4, v4, v5
	v_add_f32_e32 v4, v6, v4
	v_cndmask_b32_e32 v4, v211, v4, vcc
	v_cmp_ngt_f32_e32 vcc, -1.0, v25
	s_nop 1
	v_cndmask_b32_e32 v4, v212, v4, vcc
	v_cmp_neq_f32_e32 vcc, -1.0, v25
	s_nop 1
	v_cndmask_b32_e32 v4, v213, v4, vcc
	v_cmp_lt_f32_e64 vcc, |v25|, s2
	s_nop 1
	v_cndmask_b32_e32 v4, v4, v25, vcc
	v_sub_f32_e32 v4, v31, v4
	v_fmamk_f32 v5, v4, 0x3d800000, v30
	ds_write_b32 v2, v5 offset:31744
	s_waitcnt lgkmcnt(0)
	s_barrier
	ds_read2st64_b32 v[6:7], v0 offset0:124 offset1:125
	ds_read2st64_b32 v[8:9], v0 offset0:126 offset1:127
	ds_read2st64_b32 v[10:11], v0 offset0:128 offset1:129
	ds_read2st64_b32 v[12:13], v0 offset0:130 offset1:131
	v_cmp_lt_i32_e32 vcc, 0, v3
	s_waitcnt lgkmcnt(3)
	v_add_f32_e32 v0, 0, v6
	s_waitcnt lgkmcnt(0)
	v_cndmask_b32_e32 v2, 0, v0, vcc
	v_add_f32_e32 v4, v7, v2
	v_cmp_lt_i32_e32 vcc, 1, v3
	v_add_f32_e32 v0, v0, v7
	v_add_f32_e32 v0, v0, v8
	v_cndmask_b32_e32 v2, v2, v4, vcc
	v_add_f32_e32 v4, v8, v2
	v_cmp_lt_i32_e32 vcc, 2, v3
	v_add_f32_e32 v0, v0, v9
	v_add_f32_e32 v0, v0, v10
	v_cndmask_b32_e32 v2, v2, v4, vcc
	v_add_f32_e32 v4, v9, v2
	v_cmp_lt_i32_e32 vcc, 3, v3
	v_add_f32_e32 v0, v0, v11
	v_lshlrev_b32_e32 v7, 16, v21
	v_cndmask_b32_e32 v2, v2, v4, vcc
	v_add_f32_e32 v4, v10, v2
	v_cmp_lt_i32_e32 vcc, 4, v3
	v_lshlrev_b32_e32 v9, 16, v22
	v_lshlrev_b32_e32 v8, 16, v17
	v_cndmask_b32_e32 v2, v2, v4, vcc
	v_add_f32_e32 v4, v11, v2
	v_cmp_lt_i32_e32 vcc, 5, v3
	v_lshlrev_b32_e32 v11, 16, v24
	v_lshlrev_b32_e32 v10, 16, v20
	v_cndmask_b32_e32 v2, v2, v4, vcc
	v_add_f32_e32 v4, v12, v2
	v_cmp_lt_i32_e32 vcc, 6, v3
	s_barrier
	s_nop 0
	v_cndmask_b32_e32 v2, v2, v4, vcc
	v_add_f32_e32 v4, v13, v2
	v_cmp_lt_i32_e32 vcc, 7, v3
	s_nop 1
	v_cndmask_b32_e32 v3, v2, v4, vcc
	v_add_f32_e32 v4, v0, v12
	v_mov_b32_e32 v2, v13
	v_add_f32_e32 v6, v33, v3
	v_add_f32_e32 v25, v34, v3
	v_add_f32_e32 v26, v35, v3
	v_add_f32_e32 v27, v36, v3
	v_add_f32_e32 v28, v3, v37
	v_add_f32_e32 v29, v3, v53
	v_add_f32_e32 v30, v3, v30
	v_pk_add_f32 v[2:3], v[4:5], v[2:3]
	v_mov_b32_e32 v80, v6
	v_mov_b32_e32 v81, v25
	v_mov_b32_e32 v82, v26
	v_mov_b32_e32 v83, v27
	v_mov_b32_e32 v84, v28
	v_mov_b32_e32 v85, v29
	v_mov_b32_e32 v86, v30
	v_mov_b32_e32 v87, v3
	v_lshlrev_b32_e32 v88, 5, v202
	s_lshl_b32 s98, s30, 14
	s_add_u32 s98, s98, 0x4f28000
	s_add_u32 s98, s100, s98
	s_addc_u32 s99, s101, 0
	global_store_dwordx4 v88, v[80:83], s[98:99]
	global_store_dwordx4 v88, v[84:87], s[98:99] offset:16
	v_cmp_gt_i32_e32 vcc, 64, v18
	v_sub_f32_e32 v0, v2, v6
	v_mul_f32_e32 v0, 0x3fb8aa3b, v0
	v_exp_f32_e32 v4, v0
	v_sub_f32_e32 v0, v2, v25
	v_mul_f32_e32 v0, 0x3fb8aa3b, v0
	v_exp_f32_e32 v5, v0
	v_sub_f32_e32 v0, v2, v26
	v_lshlrev_b32_e32 v6, 16, v16
	v_mul_f32_e32 v0, 0x3fb8aa3b, v0
	v_pk_mul_f32 v[4:5], v[4:5], v[6:7]
	v_exp_f32_e32 v6, v0
	v_sub_f32_e32 v0, v2, v27
	v_mul_f32_e32 v0, 0x3fb8aa3b, v0
	v_exp_f32_e32 v7, v0
	v_sub_f32_e32 v0, v2, v28
	v_mul_f32_e32 v0, 0x3fb8aa3b, v0
	v_cvt_pk_bf16_f32 v4, v4, v5
	v_pk_mul_f32 v[6:7], v[6:7], v[8:9]
	v_exp_f32_e32 v8, v0
	v_sub_f32_e32 v0, v2, v29
	v_mul_f32_e32 v0, 0x3fb8aa3b, v0
	v_exp_f32_e32 v9, v0
	v_sub_f32_e32 v0, v2, v30
	v_cvt_pk_bf16_f32 v5, v6, v7
	v_lshlrev_b32_e32 v7, 16, v23
	v_lshlrev_b32_e32 v6, 16, v19
	v_mul_f32_e32 v0, 0x3fb8aa3b, v0
	v_pk_mul_f32 v[6:7], v[8:9], v[6:7]
	v_exp_f32_e32 v8, v0
	v_sub_f32_e32 v0, v2, v3
	v_mul_f32_e32 v0, 0x3fb8aa3b, v0
	v_exp_f32_e32 v9, v0
	v_mul_u32_u24_e32 v0, 0x90, v15
	v_lshlrev_b32_e32 v3, 4, v14
	v_cvt_pk_bf16_f32 v6, v6, v7
	v_pk_mul_f32 v[8:9], v[8:9], v[10:11]
	v_add3_u32 v0, 0, v0, v3
	v_cvt_pk_bf16_f32 v7, v8, v9
	ds_write_b128 v0, v[4:7]
	s_and_saveexec_b64 s[14:15], vcc
	s_cbranch_execz .LBB0_677
	v_mul_f32_e32 v0, 0x3fb8aa3b, v2
	s_lshl_b64 s[6:7], s[30:31], 8
	v_readlane_b32 s4, v254, 53
	v_exp_f32_e32 v0, v0
	v_readlane_b32 s5, v254, 54
	s_add_u32 s6, s4, s6
	s_addc_u32 s7, s5, s7
	v_ashrrev_i32_e32 v19, 31, v18
	v_lshl_add_u64 v[2:3], v[18:19], 2, s[6:7]
	global_store_dword v[2:3], v0, off
